# phase0 convT load loops (WIN,WGT,WGU,WDN): 8 per-thread loads + gain loads issued together, single wait (prologue de-serialisation)
# speedup vs baseline: 1.0060x; 1.0060x over previous
; template <class F>
; DI void convT(bf16* dst, int N, int K, const float* src, const float* src2, int ld, const float* gain, F cmap, bf16* tile) {
;     ...
;     for (int e = tid; e < 4096; e += NTHR) {
;       const int kk = e >> 6, nn = e & 63;
;       const int k = tk * 64 + kk, n = tn * 64 + nn;
;       const int sc = cmap(n);
;       float v = 0.f;
;       if (sc >= 0) {
;         const float* s = (sc & (1 << 28)) ? src2 : src;
;         v = s[(size_t)k * ld + (sc & ((1 << 28) - 1))];
;         if (gain) v *= gain[k];
;       }
;       tile[nn * 66 + kk] = f2bf(v);
;     }
.LBB0_15:
	s_ashr_i32 s8, s67, 31
	s_lshr_b32 s8, s8, 26
	s_add_i32 s8, s67, s8
	s_ashr_i32 s68, s8, 6
	s_andn2_b32 s8, s8, 63
	s_sub_i32 s69, s67, s8
	s_and_saveexec_b64 s[54:55], s[0:1]
	s_cbranch_execz .LBB0_21
	s_lshl_b32 s8, s69, 6
	s_cmpk_lt_u32 s8, 0x800
	v_or_b32_e32 v4, s8, v13
	s_movk_i32 s8, 0x7d0
	v_or_b32_e32 v6, 0x800, v4
	v_cmp_gt_u32_e32 vcc, s8, v4
	v_subrev_u32_e32 v5, 64, v4
	s_movk_i32 s8, 0x7c0
	v_cndmask_b32_e32 v6, -1, v6, vcc
	s_cselect_b64 vcc, -1, 0
	v_cndmask_b32_e32 v5, v5, v6, vcc
	v_cmp_gt_i32_e32 vcc, s8, v4
	s_lshl_b32 s70, s68, 6
	s_mov_b64 s[56:57], 0
	v_cndmask_b32_e32 v4, v5, v4, vcc
	v_cmp_lt_i32_e64 s[8:9], -1, v4
	v_and_b32_e32 v4, 0xfffffff, v4
	v_lshlrev_b32_e32 v8, 2, v4
	v_lshl_add_u64 v[4:5], s[50:51], 0, v[8:9]
	v_ashrrev_i32_e32 v14, 6, v0
	v_mov_b32_e32 v230, 0
	v_mov_b32_e32 v231, 0
	v_mov_b32_e32 v232, 0
	v_mov_b32_e32 v233, 0
	v_mov_b32_e32 v234, 0
	v_mov_b32_e32 v235, 0
	v_mov_b32_e32 v236, 0
	v_mov_b32_e32 v237, 0
	s_and_saveexec_b64 s[58:59], s[8:9]
	s_cbranch_execz .Lcvb1_e
	v_add_u32_e32 v6, s70, v14
	v_mad_i64_i32 v[20:21], s[72:73], v6, s63, v[4:5]
	global_load_dword v230, v[20:21], off
	v_add_u32_e32 v6, 8, v6
	v_mad_i64_i32 v[20:21], s[72:73], v6, s63, v[4:5]
	global_load_dword v231, v[20:21], off
	v_add_u32_e32 v6, 8, v6
	v_mad_i64_i32 v[20:21], s[72:73], v6, s63, v[4:5]
	global_load_dword v232, v[20:21], off
	v_add_u32_e32 v6, 8, v6
	v_mad_i64_i32 v[20:21], s[72:73], v6, s63, v[4:5]
	global_load_dword v233, v[20:21], off
	v_add_u32_e32 v6, 8, v6
	v_mad_i64_i32 v[20:21], s[72:73], v6, s63, v[4:5]
	global_load_dword v234, v[20:21], off
	v_add_u32_e32 v6, 8, v6
	v_mad_i64_i32 v[20:21], s[72:73], v6, s63, v[4:5]
	global_load_dword v235, v[20:21], off
	v_add_u32_e32 v6, 8, v6
	v_mad_i64_i32 v[20:21], s[72:73], v6, s63, v[4:5]
	global_load_dword v236, v[20:21], off
	v_add_u32_e32 v6, 8, v6
	v_mad_i64_i32 v[20:21], s[72:73], v6, s63, v[4:5]
	global_load_dword v237, v[20:21], off
	s_andn2_b64 vcc, exec, s[36:37]
	s_cbranch_vccnz .Lcvb1_e
	v_add_u32_e32 v6, s70, v14
	v_ashrrev_i32_e32 v7, 31, v6
	v_lshl_add_u64 v[6:7], v[6:7], 2, s[52:53]
	global_load_dword v238, v[6:7], off
	global_load_dword v239, v[6:7], off offset:32
	global_load_dword v240, v[6:7], off offset:64
	global_load_dword v241, v[6:7], off offset:96
	global_load_dword v242, v[6:7], off offset:128
	global_load_dword v243, v[6:7], off offset:160
	global_load_dword v244, v[6:7], off offset:192
	global_load_dword v245, v[6:7], off offset:224
	s_waitcnt vmcnt(0)
	v_mul_f32_e32 v230, v230, v238
	v_mul_f32_e32 v231, v231, v239
	v_mul_f32_e32 v232, v232, v240
	v_mul_f32_e32 v233, v233, v241
	v_mul_f32_e32 v234, v234, v242
	v_mul_f32_e32 v235, v235, v243
	v_mul_f32_e32 v236, v236, v244
	v_mul_f32_e32 v237, v237, v245
.Lcvb1_e:
	s_or_b64 exec, exec, s[58:59]
	s_waitcnt vmcnt(0)
	v_lshl_add_u32 v7, v14, 1, v17
	v_cvt_pk_bf16_f32 v230, v230, s0
	v_cvt_pk_bf16_f32 v231, v231, s0
	v_cvt_pk_bf16_f32 v232, v232, s0
	v_cvt_pk_bf16_f32 v233, v233, s0
	v_cvt_pk_bf16_f32 v234, v234, s0
	v_cvt_pk_bf16_f32 v235, v235, s0
	v_cvt_pk_bf16_f32 v236, v236, s0
	v_cvt_pk_bf16_f32 v237, v237, s0
	ds_write_b16 v7, v230
	ds_write_b16 v7, v231 offset:16
	ds_write_b16 v7, v232 offset:32
	ds_write_b16 v7, v233 offset:48
	ds_write_b16 v7, v234 offset:64
	ds_write_b16 v7, v235 offset:80
	ds_write_b16 v7, v236 offset:96
	ds_write_b16 v7, v237 offset:112

; template <class F>
; DI void convT(bf16* dst, int N, int K, const float* src, const float* src2, int ld, const float* gain, F cmap, bf16* tile) {
;     ...
;     for (int e = tid; e < 4096; e += NTHR) {
;       const int kk = e >> 6, nn = e & 63;
;       const int k = tk * 64 + kk, n = tn * 64 + nn;
;       const int sc = cmap(n);
;       float v = 0.f;
;       if (sc >= 0) {
;         const float* s = (sc & (1 << 28)) ? src2 : src;
;         v = s[(size_t)k * ld + (sc & ((1 << 28) - 1))];
;         if (gain) v *= gain[k];
;       }
;       tile[nn * 66 + kk] = f2bf(v);
;     }
.LBB0_32:
	s_mul_hi_i32 s8, s59, 0x2aaaaaab
	s_lshr_b32 s9, s8, 31
	s_ashr_i32 s56, s8, 3
	s_add_i32 s56, s56, s9
	s_mul_i32 s8, s56, 48
	s_sub_i32 s57, s59, s8
	s_and_saveexec_b64 s[8:9], s[0:1]
	s_cbranch_execz .LBB0_37
	v_lshl_or_b32 v4, s57, 6, v14
	v_ashrrev_i32_e32 v5, 31, v4
	s_lshl_b32 s66, s56, 6
	v_lshl_add_u64 v[4:5], v[4:5], 2, s[50:51]
	s_mov_b64 s[54:55], 0
	v_ashrrev_i32_e32 v13, 6, v0
	v_mov_b32_e32 v230, 0
	v_mov_b32_e32 v231, 0
	v_mov_b32_e32 v232, 0
	v_mov_b32_e32 v233, 0
	v_mov_b32_e32 v234, 0
	v_mov_b32_e32 v235, 0
	v_mov_b32_e32 v236, 0
	v_mov_b32_e32 v237, 0
	v_add_u32_e32 v6, s66, v13
	v_mad_i64_i32 v[20:21], s[68:69], v6, s63, v[4:5]
	v_add_co_u32_e32 v20, vcc, 0x3000, v20
	s_nop 1
	v_addc_co_u32_e32 v21, vcc, 0, v21, vcc
	global_load_dword v230, v[20:21], off offset:3904
	v_add_u32_e32 v6, 8, v6
	v_mad_i64_i32 v[20:21], s[68:69], v6, s63, v[4:5]
	v_add_co_u32_e32 v20, vcc, 0x3000, v20
	s_nop 1
	v_addc_co_u32_e32 v21, vcc, 0, v21, vcc
	global_load_dword v231, v[20:21], off offset:3904
	v_add_u32_e32 v6, 8, v6
	v_mad_i64_i32 v[20:21], s[68:69], v6, s63, v[4:5]
	v_add_co_u32_e32 v20, vcc, 0x3000, v20
	s_nop 1
	v_addc_co_u32_e32 v21, vcc, 0, v21, vcc
	global_load_dword v232, v[20:21], off offset:3904
	v_add_u32_e32 v6, 8, v6
	v_mad_i64_i32 v[20:21], s[68:69], v6, s63, v[4:5]
	v_add_co_u32_e32 v20, vcc, 0x3000, v20
	s_nop 1
	v_addc_co_u32_e32 v21, vcc, 0, v21, vcc
	global_load_dword v233, v[20:21], off offset:3904
	v_add_u32_e32 v6, 8, v6
	v_mad_i64_i32 v[20:21], s[68:69], v6, s63, v[4:5]
	v_add_co_u32_e32 v20, vcc, 0x3000, v20
	s_nop 1
	v_addc_co_u32_e32 v21, vcc, 0, v21, vcc
	global_load_dword v234, v[20:21], off offset:3904
	v_add_u32_e32 v6, 8, v6
	v_mad_i64_i32 v[20:21], s[68:69], v6, s63, v[4:5]
	v_add_co_u32_e32 v20, vcc, 0x3000, v20
	s_nop 1
	v_addc_co_u32_e32 v21, vcc, 0, v21, vcc
	global_load_dword v235, v[20:21], off offset:3904
	v_add_u32_e32 v6, 8, v6
	v_mad_i64_i32 v[20:21], s[68:69], v6, s63, v[4:5]
	v_add_co_u32_e32 v20, vcc, 0x3000, v20
	s_nop 1
	v_addc_co_u32_e32 v21, vcc, 0, v21, vcc
	global_load_dword v236, v[20:21], off offset:3904
	v_add_u32_e32 v6, 8, v6
	v_mad_i64_i32 v[20:21], s[68:69], v6, s63, v[4:5]
	v_add_co_u32_e32 v20, vcc, 0x3000, v20
	s_nop 1
	v_addc_co_u32_e32 v21, vcc, 0, v21, vcc
	global_load_dword v237, v[20:21], off offset:3904
	s_andn2_b64 vcc, exec, s[36:37]
	s_cbranch_vccnz .Lcvb2_e
	v_add_u32_e32 v6, s66, v13
	v_ashrrev_i32_e32 v7, 31, v6
	v_lshl_add_u64 v[6:7], v[6:7], 2, s[52:53]
	global_load_dword v238, v[6:7], off
	global_load_dword v239, v[6:7], off offset:32
	global_load_dword v240, v[6:7], off offset:64
	global_load_dword v241, v[6:7], off offset:96
	global_load_dword v242, v[6:7], off offset:128
	global_load_dword v243, v[6:7], off offset:160
	global_load_dword v244, v[6:7], off offset:192
	global_load_dword v245, v[6:7], off offset:224
	s_waitcnt vmcnt(0)
	v_mul_f32_e32 v230, v230, v238
	v_mul_f32_e32 v231, v231, v239
	v_mul_f32_e32 v232, v232, v240
	v_mul_f32_e32 v233, v233, v241
	v_mul_f32_e32 v234, v234, v242
	v_mul_f32_e32 v235, v235, v243
	v_mul_f32_e32 v236, v236, v244
	v_mul_f32_e32 v237, v237, v245
.Lcvb2_e:
	s_waitcnt vmcnt(0)
	v_lshl_add_u32 v7, v13, 1, v15
	v_cvt_pk_bf16_f32 v230, v230, s0
	v_cvt_pk_bf16_f32 v231, v231, s0
	v_cvt_pk_bf16_f32 v232, v232, s0
	v_cvt_pk_bf16_f32 v233, v233, s0
	v_cvt_pk_bf16_f32 v234, v234, s0
	v_cvt_pk_bf16_f32 v235, v235, s0
	v_cvt_pk_bf16_f32 v236, v236, s0
	v_cvt_pk_bf16_f32 v237, v237, s0
	ds_write_b16 v7, v230
	ds_write_b16 v7, v231 offset:16
	ds_write_b16 v7, v232 offset:32
	ds_write_b16 v7, v233 offset:48
	ds_write_b16 v7, v234 offset:64
	ds_write_b16 v7, v235 offset:80
	ds_write_b16 v7, v236 offset:96
	ds_write_b16 v7, v237 offset:112

; template <class F>
; DI void convT(bf16* dst, int N, int K, const float* src, const float* src2, int ld, const float* gain, F cmap, bf16* tile) {
;     ...
;     for (int e = tid; e < 4096; e += NTHR) {
;       const int kk = e >> 6, nn = e & 63;
;       const int k = tk * 64 + kk, n = tn * 64 + nn;
;       const int sc = cmap(n);
;       float v = 0.f;
;       if (sc >= 0) {
;         const float* s = (sc & (1 << 28)) ? src2 : src;
;         v = s[(size_t)k * ld + (sc & ((1 << 28) - 1))];
;         if (gain) v *= gain[k];
;       }
;       tile[nn * 66 + kk] = f2bf(v);
;     }
.LBB0_160:
	s_mul_hi_i32 s10, s59, 0x2e8ba2e9
	s_lshr_b32 s11, s10, 31
	s_ashr_i32 s66, s10, 4
	s_add_i32 s66, s66, s11
	s_mul_i32 s10, s66, 0x58
	s_sub_i32 s67, s59, s10
	s_and_saveexec_b64 s[52:53], s[0:1]
	s_cbranch_execz .LBB0_166
	v_lshl_or_b32 v4, s67, 6, v17
	v_ashrrev_i32_e32 v4, 1, v4
	v_and_b32_e32 v4, -16, v4
	v_or_b32_e32 v5, v4, v13
	v_add_u32_e32 v4, v18, v4
	v_or_b32_e32 v4, 0x10000000, v4
	v_cndmask_b32_e64 v6, v4, v5, s[4:5]
	v_and_b32_e32 v4, 0x10000000, v6
	v_mov_b32_e32 v5, s19
	v_mov_b32_e32 v7, s17
	v_cmp_eq_u32_e32 vcc, 0, v4
	v_mov_b32_e32 v4, s18
	v_cmp_lt_i32_e64 s[10:11], -1, v6
	v_cndmask_b32_e32 v5, v5, v7, vcc
	v_mov_b32_e32 v7, s16
	v_cndmask_b32_e32 v4, v4, v7, vcc
	v_and_b32_e32 v6, 0xfffffff, v6
	v_lshl_add_u64 v[4:5], v[4:5], 0, s[42:43]
	v_lshlrev_b32_e32 v8, 2, v6
	s_lshl_b32 s68, s66, 6
	v_lshl_add_u64 v[4:5], v[4:5], 0, v[8:9]
	s_mov_b64 s[54:55], 0
	s_movk_i32 s69, 0x2c00
	v_ashrrev_i32_e32 v14, 6, v0
	v_mov_b32_e32 v230, 0
	v_mov_b32_e32 v231, 0
	v_mov_b32_e32 v232, 0
	v_mov_b32_e32 v233, 0
	v_mov_b32_e32 v234, 0
	v_mov_b32_e32 v235, 0
	v_mov_b32_e32 v236, 0
	v_mov_b32_e32 v237, 0
	s_and_saveexec_b64 s[56:57], s[10:11]
	s_cbranch_execz .Lcvb3_e
	v_add_u32_e32 v6, s68, v14
	v_mad_i64_i32 v[22:23], s[70:71], v6, s69, v[4:5]
	global_load_dword v230, v[22:23], off
	v_add_u32_e32 v6, 8, v6
	v_mad_i64_i32 v[22:23], s[70:71], v6, s69, v[4:5]
	global_load_dword v231, v[22:23], off
	v_add_u32_e32 v6, 8, v6
	v_mad_i64_i32 v[22:23], s[70:71], v6, s69, v[4:5]
	global_load_dword v232, v[22:23], off
	v_add_u32_e32 v6, 8, v6
	v_mad_i64_i32 v[22:23], s[70:71], v6, s69, v[4:5]
	global_load_dword v233, v[22:23], off
	v_add_u32_e32 v6, 8, v6
	v_mad_i64_i32 v[22:23], s[70:71], v6, s69, v[4:5]
	global_load_dword v234, v[22:23], off
	v_add_u32_e32 v6, 8, v6
	v_mad_i64_i32 v[22:23], s[70:71], v6, s69, v[4:5]
	global_load_dword v235, v[22:23], off
	v_add_u32_e32 v6, 8, v6
	v_mad_i64_i32 v[22:23], s[70:71], v6, s69, v[4:5]
	global_load_dword v236, v[22:23], off
	v_add_u32_e32 v6, 8, v6
	v_mad_i64_i32 v[22:23], s[70:71], v6, s69, v[4:5]
	global_load_dword v237, v[22:23], off
	s_andn2_b64 vcc, exec, s[44:45]
	s_cbranch_vccnz .Lcvb3_e
	v_add_u32_e32 v6, s68, v14
	v_ashrrev_i32_e32 v7, 31, v6
	v_lshl_add_u64 v[6:7], v[6:7], 2, s[50:51]
	global_load_dword v238, v[6:7], off
	global_load_dword v239, v[6:7], off offset:32
	global_load_dword v240, v[6:7], off offset:64
	global_load_dword v241, v[6:7], off offset:96
	global_load_dword v242, v[6:7], off offset:128
	global_load_dword v243, v[6:7], off offset:160
	global_load_dword v244, v[6:7], off offset:192
	global_load_dword v245, v[6:7], off offset:224
	s_waitcnt vmcnt(0)
	v_mul_f32_e32 v230, v230, v238
	v_mul_f32_e32 v231, v231, v239
	v_mul_f32_e32 v232, v232, v240
	v_mul_f32_e32 v233, v233, v241
	v_mul_f32_e32 v234, v234, v242
	v_mul_f32_e32 v235, v235, v243
	v_mul_f32_e32 v236, v236, v244
	v_mul_f32_e32 v237, v237, v245
.Lcvb3_e:
	s_or_b64 exec, exec, s[56:57]
	s_waitcnt vmcnt(0)
	v_lshl_add_u32 v7, v14, 1, v19
	v_cvt_pk_bf16_f32 v230, v230, s0
	v_cvt_pk_bf16_f32 v231, v231, s0
	v_cvt_pk_bf16_f32 v232, v232, s0
	v_cvt_pk_bf16_f32 v233, v233, s0
	v_cvt_pk_bf16_f32 v234, v234, s0
	v_cvt_pk_bf16_f32 v235, v235, s0
	v_cvt_pk_bf16_f32 v236, v236, s0
	v_cvt_pk_bf16_f32 v237, v237, s0
	ds_write_b16 v7, v230
	ds_write_b16 v7, v231 offset:16
	ds_write_b16 v7, v232 offset:32
	ds_write_b16 v7, v233 offset:48
	ds_write_b16 v7, v234 offset:64
	ds_write_b16 v7, v235 offset:80
	ds_write_b16 v7, v236 offset:96
	ds_write_b16 v7, v237 offset:112

; template <class F>
; DI void convT(bf16* dst, int N, int K, const float* src, const float* src2, int ld, const float* gain, F cmap, bf16* tile) {
;     ...
;     for (int e = tid; e < 4096; e += NTHR) {
;       const int kk = e >> 6, nn = e & 63;
;       const int k = tk * 64 + kk, n = tn * 64 + nn;
;       const int sc = cmap(n);
;       float v = 0.f;
;       if (sc >= 0) {
;         const float* s = (sc & (1 << 28)) ? src2 : src;
;         v = s[(size_t)k * ld + (sc & ((1 << 28) - 1))];
;         if (gain) v *= gain[k];
;       }
;       tile[nn * 66 + kk] = f2bf(v);
;     }
.LBB0_177:
	s_ashr_i32 s46, s52, 31
	s_lshr_b32 s46, s46, 28
	s_add_i32 s46, s52, s46
	s_ashr_i32 s54, s46, 4
	s_and_b32 s46, s46, -16
	s_sub_i32 s53, s52, s46
	s_and_saveexec_b64 s[46:47], s[0:1]
	s_cbranch_execz .LBB0_183
	s_cmp_gt_i32 s53, -1
	s_cselect_b64 s[48:49], -1, 0
	s_lshl_b32 s50, s53, 6
	s_and_b32 s50, s50, 0xfffffc0
	v_or_b32_e32 v4, s50, v13
	v_lshlrev_b32_e32 v8, 2, v4
	s_lshl_b32 s55, s54, 6
	v_lshl_add_u64 v[4:5], s[10:11], 0, v[8:9]
	s_mov_b64 s[50:51], 0
	v_ashrrev_i32_e32 v7, 6, v0
	v_mov_b32_e32 v230, 0
	v_mov_b32_e32 v231, 0
	v_mov_b32_e32 v232, 0
	v_mov_b32_e32 v233, 0
	v_mov_b32_e32 v234, 0
	v_mov_b32_e32 v235, 0
	v_mov_b32_e32 v236, 0
	v_mov_b32_e32 v237, 0
	s_andn2_b64 vcc, exec, s[48:49]
	s_cbranch_vccnz .Lcvb4_e
	v_add_u32_e32 v6, s55, v7
	v_ashrrev_i32_e32 v15, 31, v6
	v_mov_b32_e32 v14, v6
	v_lshlrev_b64 v[14:15], 12, v[14:15]
	v_lshl_add_u64 v[14:15], v[4:5], 0, v[14:15]
	global_load_dword v230, v[14:15], off
	v_add_u32_e32 v6, 8, v6
	v_ashrrev_i32_e32 v15, 31, v6
	v_mov_b32_e32 v14, v6
	v_lshlrev_b64 v[14:15], 12, v[14:15]
	v_lshl_add_u64 v[14:15], v[4:5], 0, v[14:15]
	global_load_dword v231, v[14:15], off
	v_add_u32_e32 v6, 8, v6
	v_ashrrev_i32_e32 v15, 31, v6
	v_mov_b32_e32 v14, v6
	v_lshlrev_b64 v[14:15], 12, v[14:15]
	v_lshl_add_u64 v[14:15], v[4:5], 0, v[14:15]
	global_load_dword v232, v[14:15], off
	v_add_u32_e32 v6, 8, v6
	v_ashrrev_i32_e32 v15, 31, v6
	v_mov_b32_e32 v14, v6
	v_lshlrev_b64 v[14:15], 12, v[14:15]
	v_lshl_add_u64 v[14:15], v[4:5], 0, v[14:15]
	global_load_dword v233, v[14:15], off
	v_add_u32_e32 v6, 8, v6
	v_ashrrev_i32_e32 v15, 31, v6
	v_mov_b32_e32 v14, v6
	v_lshlrev_b64 v[14:15], 12, v[14:15]
	v_lshl_add_u64 v[14:15], v[4:5], 0, v[14:15]
	global_load_dword v234, v[14:15], off
	v_add_u32_e32 v6, 8, v6
	v_ashrrev_i32_e32 v15, 31, v6
	v_mov_b32_e32 v14, v6
	v_lshlrev_b64 v[14:15], 12, v[14:15]
	v_lshl_add_u64 v[14:15], v[4:5], 0, v[14:15]
	global_load_dword v235, v[14:15], off
	v_add_u32_e32 v6, 8, v6
	v_ashrrev_i32_e32 v15, 31, v6
	v_mov_b32_e32 v14, v6
	v_lshlrev_b64 v[14:15], 12, v[14:15]
	v_lshl_add_u64 v[14:15], v[4:5], 0, v[14:15]
	global_load_dword v236, v[14:15], off
	v_add_u32_e32 v6, 8, v6
	v_ashrrev_i32_e32 v15, 31, v6
	v_mov_b32_e32 v14, v6
	v_lshlrev_b64 v[14:15], 12, v[14:15]
	v_lshl_add_u64 v[14:15], v[4:5], 0, v[14:15]
	global_load_dword v237, v[14:15], off
.Lcvb4_e:
	s_waitcnt vmcnt(0)
	v_lshl_add_u32 v7, v7, 1, v17
	v_cvt_pk_bf16_f32 v230, v230, s0
	v_cvt_pk_bf16_f32 v231, v231, s0
	v_cvt_pk_bf16_f32 v232, v232, s0
	v_cvt_pk_bf16_f32 v233, v233, s0
	v_cvt_pk_bf16_f32 v234, v234, s0
	v_cvt_pk_bf16_f32 v235, v235, s0
	v_cvt_pk_bf16_f32 v236, v236, s0
	v_cvt_pk_bf16_f32 v237, v237, s0
	ds_write_b16 v7, v230
	ds_write_b16 v7, v231 offset:16
	ds_write_b16 v7, v232 offset:32
	ds_write_b16 v7, v233 offset:48
	ds_write_b16 v7, v234 offset:64
	ds_write_b16 v7, v235 offset:80
	ds_write_b16 v7, v236 offset:96
	ds_write_b16 v7, v237 offset:112
